# nt cache hint on once-read streams only: phase-0 x copy loads and the LayerNorm row loads
# speedup vs baseline: 1.0072x; 1.0072x over previous
.LBB0_85:
	v_add_u32_e32 v42, s42, v48
	s_mov_b32 s0, 0x8000
	v_ashrrev_i32_e32 v49, 31, v48
	v_cmp_gt_i32_e64 s[38:39], s0, v42
	v_lshlrev_b64 v[2:3], 12, v[48:49]
	v_lshl_add_u64 v[44:45], v[34:35], 0, v[2:3]
	v_cndmask_b32_e64 v2, v48, v42, s[38:39]
	v_ashrrev_i32_e32 v3, 31, v2
	v_lshlrev_b64 v[2:3], 12, v[2:3]
	v_lshl_add_u64 v[2:3], v[34:35], 0, v[2:3]
	global_load_dwordx4 v[30:33], v[44:45], off nt
	global_load_dwordx4 v[26:29], v[44:45], off offset:1024 nt
	global_load_dwordx4 v[22:25], v[44:45], off offset:2048 nt
	global_load_dwordx4 v[18:21], v[44:45], off offset:3072 nt
	global_load_dwordx4 v[14:17], v[2:3], off nt
	global_load_dwordx4 v[10:13], v[2:3], off offset:1024 nt
	global_load_dwordx4 v[6:9], v[2:3], off offset:2048 nt
	s_nop 0
	global_load_dwordx4 v[2:5], v[2:3], off offset:3072 nt
	s_mov_b32 s0, 0x3c800000
	s_mov_b32 s1, 0x3a800000
	s_mov_b32 s0, s1
	s_waitcnt vmcnt(6)
	v_pk_add_f32 v[50:51], v[30:31], v[26:27]
	v_pk_add_f32 v[46:47], v[32:33], v[28:29]
	s_waitcnt vmcnt(5)
	v_pk_add_f32 v[50:51], v[50:51], v[22:23]
	v_pk_add_f32 v[46:47], v[46:47], v[24:25]
	s_waitcnt vmcnt(4)
	v_pk_add_f32 v[50:51], v[50:51], v[18:19]
	v_pk_add_f32 v[46:47], v[46:47], v[20:21]
	v_add_f32_e32 v43, v50, v51
	v_add_f32_e32 v43, v46, v43
	s_waitcnt vmcnt(2)
	v_pk_add_f32 v[54:55], v[14:15], v[10:11]
	v_add_f32_e32 v43, v47, v43
	v_pk_add_f32 v[52:53], v[16:17], v[12:13]
	s_waitcnt vmcnt(1)
	v_pk_add_f32 v[54:55], v[54:55], v[6:7]
	v_pk_add_f32 v[52:53], v[52:53], v[8:9]
	s_waitcnt vmcnt(0)
	v_pk_add_f32 v[54:55], v[54:55], v[2:3]
	v_pk_add_f32 v[52:53], v[52:53], v[4:5]
	v_add_f32_e32 v46, v54, v55
	v_add_f32_e32 v46, v52, v46
	v_add_f32_e32 v46, v53, v46
	v_mov_b32_e32 v47, v43
	v_mov_b32_e32 v132, v46
	s_nop 1
	v_permlane32_swap_b32_e32 v43, v47
	v_permlane32_swap_b32_e32 v46, v132
	v_add_f32_e32 v43, v43, v47
	v_add_f32_e32 v46, v46, v132
	v_mov_b32_e32 v47, v43
	v_mov_b32_e32 v132, v46
	s_nop 1
	v_permlane16_swap_b32_e32 v43, v47
	v_permlane16_swap_b32_e32 v46, v132
	v_add_f32_e32 v43, v43, v47
	v_add_f32_e32 v46, v46, v132
	s_nop 1
	v_add_f32_dpp v43, v43, v43 row_ror:8 row_mask:0xf bank_mask:0xf
	v_add_f32_dpp v46, v46, v46 row_ror:8 row_mask:0xf bank_mask:0xf
	s_nop 0
	v_add_f32_dpp v43, v43, v43 row_ror:4 row_mask:0xf bank_mask:0xf
	v_add_f32_dpp v46, v46, v46 row_ror:4 row_mask:0xf bank_mask:0xf
	s_nop 0
	v_add_f32_dpp v43, v43, v43 quad_perm:[2,3,0,1] row_mask:0xf bank_mask:0xf
	v_add_f32_dpp v46, v46, v46 quad_perm:[2,3,0,1] row_mask:0xf bank_mask:0xf
	s_nop 0
	v_add_f32_dpp v61, v43, v43 quad_perm:[1,0,3,2] row_mask:0xf bank_mask:0xf
	v_add_f32_dpp v43, v46, v46 quad_perm:[1,0,3,2] row_mask:0xf bank_mask:0xf
	v_fmamk_f32 v27, v61, 0xba800000, v27
	v_fmac_f32_e32 v26, 0xba800000, v61
	v_fmamk_f32 v63, v61, 0xba800000, v33
	v_fmamk_f32 v62, v61, 0xba800000, v32
	v_fmamk_f32 v11, v43, 0xba800000, v11
	v_fmac_f32_e32 v10, 0xba800000, v43
	v_fmamk_f32 v31, v61, 0xba800000, v31
	v_fmac_f32_e32 v30, 0xba800000, v61
	v_fmamk_f32 v59, v61, 0xba800000, v29
	v_fmamk_f32 v58, v61, 0xba800000, v28
	v_fmamk_f32 v15, v43, 0xba800000, v15
	v_fmac_f32_e32 v14, 0xba800000, v43
	v_fmamk_f32 v51, v43, 0xba800000, v13
	v_fmamk_f32 v50, v43, 0xba800000, v12
	v_fmamk_f32 v33, v43, 0xba800000, v5
	v_fmamk_f32 v32, v43, 0xba800000, v4
	v_pk_mul_f32 v[4:5], v[26:27], v[26:27]
	v_pk_mul_f32 v[12:13], v[10:11], v[10:11]
	v_fmamk_f32 v23, v61, 0xba800000, v23
	v_fmac_f32_e32 v22, 0xba800000, v61
	v_fmamk_f32 v53, v43, 0xba800000, v17
	v_fmamk_f32 v52, v43, 0xba800000, v16
	v_fmamk_f32 v47, v43, 0xba800000, v9
	v_fmamk_f32 v46, v43, 0xba800000, v8
	v_fmamk_f32 v7, v43, 0xba800000, v7
	v_fmac_f32_e32 v6, 0xba800000, v43
	v_pk_mul_f32 v[8:9], v[58:59], v[58:59]
	v_pk_fma_f32 v[4:5], v[30:31], v[30:31], v[4:5]
	v_pk_mul_f32 v[16:17], v[50:51], v[50:51]
	v_pk_fma_f32 v[12:13], v[14:15], v[14:15], v[12:13]
	v_fmamk_f32 v57, v61, 0xba800000, v25
	v_fmamk_f32 v56, v61, 0xba800000, v24
	v_fmamk_f32 v19, v61, 0xba800000, v19
	v_fmac_f32_e32 v18, 0xba800000, v61
	v_fmamk_f32 v3, v43, 0xba800000, v3
	v_fmac_f32_e32 v2, 0xba800000, v43
	v_pk_fma_f32 v[8:9], v[62:63], v[62:63], v[8:9]
	v_pk_fma_f32 v[4:5], v[22:23], v[22:23], v[4:5]
	v_pk_fma_f32 v[16:17], v[52:53], v[52:53], v[16:17]
	v_pk_fma_f32 v[12:13], v[6:7], v[6:7], v[12:13]
	v_fmamk_f32 v55, v61, 0xba800000, v21
	v_fmamk_f32 v54, v61, 0xba800000, v20
	v_pk_fma_f32 v[8:9], v[56:57], v[56:57], v[8:9]
	v_pk_fma_f32 v[4:5], v[18:19], v[18:19], v[4:5]
	v_pk_fma_f32 v[16:17], v[46:47], v[46:47], v[16:17]
	v_pk_fma_f32 v[12:13], v[2:3], v[2:3], v[12:13]
	v_pk_fma_f32 v[8:9], v[54:55], v[54:55], v[8:9]
	v_pk_fma_f32 v[16:17], v[32:33], v[32:33], v[16:17]
	v_mov_b32_e32 v20, v12
	v_mov_b32_e32 v21, v4
	v_mov_b32_e32 v4, v13
	v_pk_add_f32 v[4:5], v[20:21], v[4:5]
	v_mov_b32_e32 v12, v16
	v_mov_b32_e32 v13, v8
	v_pk_add_f32 v[4:5], v[12:13], v[4:5]
	v_mov_b32_e32 v8, v17
	v_pk_add_f32 v[4:5], v[8:9], v[4:5]
	v_mov_b32_e32 v8, v4
	v_mov_b32_e32 v9, v5
	s_nop 1
	v_permlane32_swap_b32_e32 v4, v8
	v_permlane32_swap_b32_e32 v5, v9
	v_pk_add_f32 v[4:5], v[4:5], v[8:9]
	v_mov_b32_e32 v8, v4
	v_mov_b32_e32 v9, v5
	s_nop 1
	v_permlane16_swap_b32_e32 v4, v8
	v_permlane16_swap_b32_e32 v5, v9
	v_pk_add_f32 v[4:5], v[4:5], v[8:9]
	s_nop 1
	v_add_f32_dpp v4, v4, v4 row_ror:8 row_mask:0xf bank_mask:0xf
	v_add_f32_dpp v5, v5, v5 row_ror:8 row_mask:0xf bank_mask:0xf
	s_nop 0
	v_add_f32_dpp v4, v4, v4 row_ror:4 row_mask:0xf bank_mask:0xf
	v_add_f32_dpp v5, v5, v5 row_ror:4 row_mask:0xf bank_mask:0xf
	s_nop 0
	v_add_f32_dpp v4, v4, v4 quad_perm:[2,3,0,1] row_mask:0xf bank_mask:0xf
	v_add_f32_dpp v5, v5, v5 quad_perm:[2,3,0,1] row_mask:0xf bank_mask:0xf
	s_nop 0
	v_add_f32_dpp v4, v4, v4 quad_perm:[1,0,3,2] row_mask:0xf bank_mask:0xf
	v_add_f32_dpp v5, v5, v5 quad_perm:[1,0,3,2] row_mask:0xf bank_mask:0xf
	v_mov_b32_e32 v8, 0x3727c5ac
	v_pk_fma_f32 v[8:9], v[4:5], s[0:1], v[8:9] op_sel_hi:[1,0,0]
	s_mov_b32 s0, 0x800000
	v_mul_f32_e32 v4, 0x4b800000, v9
	v_cmp_gt_f32_e32 vcc, s0, v8
	v_cmp_gt_f32_e64 s[0:1], s0, v9
	s_nop 1
	v_cndmask_b32_e64 v4, v9, v4, s[0:1]
	v_rsq_f32_e32 v4, v4
	s_nop 0
	v_mul_f32_e32 v5, 0x45800000, v4
	v_cndmask_b32_e64 v4, v4, v5, s[0:1]
	v_mul_f32_e32 v5, 0x4b800000, v8
	v_cndmask_b32_e32 v5, v8, v5, vcc
	v_rsq_f32_e32 v5, v5
	s_nop 0
	v_mul_f32_e32 v8, 0x45800000, v5
	v_cndmask_b32_e32 v60, v5, v8, vcc
	s_and_saveexec_b64 s[0:1], s[46:47]
	s_cbranch_execz .LBB0_88
	v_readlane_b32 s4, v254, 30
	v_readlane_b32 s5, v254, 31
	v_mul_f32_e32 v12, 0x3a800000, v61
	v_mov_b32_e32 v13, v4
	v_lshl_add_u64 v[8:9], v[48:49], 3, s[4:5]
	global_store_dwordx2 v[8:9], v[12:13], off
	s_and_b64 exec, exec, s[38:39]
	s_cbranch_execz .LBB0_88
	v_mul_f32_e32 v12, 0x3a800000, v43
	v_lshl_add_u64 v[8:9], s[42:43], 3, v[8:9]
	v_mov_b32_e32 v13, v60
	global_store_dwordx2 v[8:9], v[12:13], off

.LBB0_146:
	v_add_u32_e32 v42, s42, v44
	s_mov_b32 s0, 0x8000
	v_cmp_gt_i32_e64 s[38:39], s0, v42
	v_ashrrev_i32_e32 v45, 31, v44
	v_lshlrev_b64 v[2:3], 12, v[44:45]
	v_cndmask_b32_e64 v4, v44, v42, s[38:39]
	v_ashrrev_i32_e32 v5, 31, v4
	v_lshlrev_b64 v[4:5], 12, v[4:5]
	v_lshl_add_u64 v[2:3], v[34:35], 0, v[2:3]
	v_lshl_add_u64 v[4:5], v[34:35], 0, v[4:5]
	global_load_dwordx4 v[30:33], v[2:3], off nt
	global_load_dwordx4 v[26:29], v[2:3], off offset:1024 nt
	global_load_dwordx4 v[22:25], v[2:3], off offset:2048 nt
	global_load_dwordx4 v[18:21], v[2:3], off offset:3072 nt
	global_load_dwordx4 v[14:17], v[4:5], off nt
	global_load_dwordx4 v[10:13], v[4:5], off offset:1024 nt
	global_load_dwordx4 v[6:9], v[4:5], off offset:2048 nt
	s_nop 0
	global_load_dwordx4 v[2:5], v[4:5], off offset:3072 nt
	s_mov_b32 s0, 0x3c800000
	s_mov_b32 s1, 0x3a800000
	s_mov_b32 s0, s1
	s_mov_b32 s2, 0x800000
	s_waitcnt vmcnt(6)
	v_pk_add_f32 v[48:49], v[30:31], v[26:27]
	v_pk_add_f32 v[46:47], v[32:33], v[28:29]
	s_waitcnt vmcnt(5)
	v_pk_add_f32 v[48:49], v[48:49], v[22:23]
	v_pk_add_f32 v[46:47], v[46:47], v[24:25]
	s_waitcnt vmcnt(4)
	v_pk_add_f32 v[48:49], v[48:49], v[18:19]
	v_pk_add_f32 v[46:47], v[46:47], v[20:21]
	v_add_f32_e32 v0, v48, v49
	v_add_f32_e32 v0, v46, v0
	s_waitcnt vmcnt(2)
	v_pk_add_f32 v[58:59], v[14:15], v[10:11]
	v_add_f32_e32 v0, v47, v0
	v_pk_add_f32 v[56:57], v[16:17], v[12:13]
	s_waitcnt vmcnt(1)
	v_pk_add_f32 v[58:59], v[58:59], v[6:7]
	v_pk_add_f32 v[56:57], v[56:57], v[8:9]
	s_waitcnt vmcnt(0)
	v_pk_add_f32 v[58:59], v[58:59], v[2:3]
	v_pk_add_f32 v[56:57], v[56:57], v[4:5]
	v_add_f32_e32 v43, v58, v59
	v_add_f32_e32 v43, v56, v43
	v_add_f32_e32 v43, v57, v43
	v_mov_b32_e32 v46, v0
	v_mov_b32_e32 v132, v43
	s_nop 1
	v_permlane32_swap_b32_e32 v0, v46
	v_permlane32_swap_b32_e32 v43, v132
	v_add_f32_e32 v0, v0, v46
	v_add_f32_e32 v43, v43, v132
	v_mov_b32_e32 v46, v0
	v_mov_b32_e32 v132, v43
	s_nop 1
	v_permlane16_swap_b32_e32 v0, v46
	v_permlane16_swap_b32_e32 v43, v132
	v_add_f32_e32 v0, v0, v46
	v_add_f32_e32 v43, v43, v132
	s_nop 1
	v_add_f32_dpp v0, v0, v0 row_ror:8 row_mask:0xf bank_mask:0xf
	v_add_f32_dpp v43, v43, v43 row_ror:8 row_mask:0xf bank_mask:0xf
	s_nop 0
	v_add_f32_dpp v0, v0, v0 row_ror:4 row_mask:0xf bank_mask:0xf
	v_add_f32_dpp v43, v43, v43 row_ror:4 row_mask:0xf bank_mask:0xf
	s_nop 0
	v_add_f32_dpp v0, v0, v0 quad_perm:[2,3,0,1] row_mask:0xf bank_mask:0xf
	v_add_f32_dpp v43, v43, v43 quad_perm:[2,3,0,1] row_mask:0xf bank_mask:0xf
	s_nop 0
	v_add_f32_dpp v46, v0, v0 quad_perm:[1,0,3,2] row_mask:0xf bank_mask:0xf
	v_add_f32_dpp v43, v43, v43 quad_perm:[1,0,3,2] row_mask:0xf bank_mask:0xf
	v_fmamk_f32 v27, v46, 0xba800000, v27
	v_fmac_f32_e32 v26, 0xba800000, v46
	v_fmamk_f32 v31, v46, 0xba800000, v31
	v_fmac_f32_e32 v30, 0xba800000, v46
	v_fmamk_f32 v11, v43, 0xba800000, v11
	v_fmac_f32_e32 v10, 0xba800000, v43
	v_fmamk_f32 v29, v46, 0xba800000, v29
	v_fmamk_f32 v28, v46, 0xba800000, v28
	v_fmamk_f32 v15, v43, 0xba800000, v15
	v_fmac_f32_e32 v14, 0xba800000, v43
	v_fmamk_f32 v13, v43, 0xba800000, v13
	v_fmamk_f32 v12, v43, 0xba800000, v12
	v_pk_mul_f32 v[48:49], v[26:27], v[26:27]
	v_pk_mul_f32 v[58:59], v[10:11], v[10:11]
	v_fmamk_f32 v33, v46, 0xba800000, v33
	v_fmamk_f32 v32, v46, 0xba800000, v32
	v_fmamk_f32 v23, v46, 0xba800000, v23
	v_fmac_f32_e32 v22, 0xba800000, v46
	v_fmamk_f32 v17, v43, 0xba800000, v17
	v_fmamk_f32 v16, v43, 0xba800000, v16
	v_fmamk_f32 v7, v43, 0xba800000, v7
	v_fmac_f32_e32 v6, 0xba800000, v43
	v_pk_mul_f32 v[56:57], v[28:29], v[28:29]
	v_pk_fma_f32 v[48:49], v[30:31], v[30:31], v[48:49]
	v_pk_mul_f32 v[60:61], v[12:13], v[12:13]
	v_pk_fma_f32 v[58:59], v[14:15], v[14:15], v[58:59]
	v_fmamk_f32 v25, v46, 0xba800000, v25
	v_fmamk_f32 v24, v46, 0xba800000, v24
	v_fmamk_f32 v19, v46, 0xba800000, v19
	v_fmac_f32_e32 v18, 0xba800000, v46
	v_fmamk_f32 v9, v43, 0xba800000, v9
	v_fmamk_f32 v8, v43, 0xba800000, v8
	v_fmamk_f32 v3, v43, 0xba800000, v3
	v_fmac_f32_e32 v2, 0xba800000, v43
	v_pk_fma_f32 v[56:57], v[32:33], v[32:33], v[56:57]
	v_pk_fma_f32 v[48:49], v[22:23], v[22:23], v[48:49]
	v_pk_fma_f32 v[60:61], v[16:17], v[16:17], v[60:61]
	v_pk_fma_f32 v[58:59], v[6:7], v[6:7], v[58:59]
	v_fmamk_f32 v21, v46, 0xba800000, v21
	v_fmamk_f32 v20, v46, 0xba800000, v20
	v_fmamk_f32 v5, v43, 0xba800000, v5
	v_fmamk_f32 v4, v43, 0xba800000, v4
	v_pk_fma_f32 v[56:57], v[24:25], v[24:25], v[56:57]
	v_pk_fma_f32 v[48:49], v[18:19], v[18:19], v[48:49]
	v_pk_fma_f32 v[60:61], v[8:9], v[8:9], v[60:61]
	v_pk_fma_f32 v[58:59], v[2:3], v[2:3], v[58:59]
	v_pk_fma_f32 v[56:57], v[20:21], v[20:21], v[56:57]
	v_pk_fma_f32 v[60:61], v[4:5], v[4:5], v[60:61]
	v_mov_b32_e32 v62, v58
	v_mov_b32_e32 v63, v48
	v_mov_b32_e32 v48, v59
	v_pk_add_f32 v[48:49], v[62:63], v[48:49]
	v_mov_b32_e32 v58, v60
	v_mov_b32_e32 v59, v56
	v_pk_add_f32 v[48:49], v[58:59], v[48:49]
	v_mov_b32_e32 v56, v61
	v_pk_add_f32 v[48:49], v[56:57], v[48:49]
	v_mov_b32_e32 v56, v48
	v_mov_b32_e32 v57, v49
	s_nop 1
	v_permlane32_swap_b32_e32 v48, v56
	v_permlane32_swap_b32_e32 v49, v57
	v_pk_add_f32 v[48:49], v[48:49], v[56:57]
	v_mov_b32_e32 v56, v48
	v_mov_b32_e32 v57, v49
	s_nop 1
	v_permlane16_swap_b32_e32 v48, v56
	v_permlane16_swap_b32_e32 v49, v57
	v_pk_add_f32 v[48:49], v[48:49], v[56:57]
	s_nop 1
	v_add_f32_dpp v48, v48, v48 row_ror:8 row_mask:0xf bank_mask:0xf
	v_add_f32_dpp v49, v49, v49 row_ror:8 row_mask:0xf bank_mask:0xf
	s_nop 0
	v_add_f32_dpp v48, v48, v48 row_ror:4 row_mask:0xf bank_mask:0xf
	v_add_f32_dpp v49, v49, v49 row_ror:4 row_mask:0xf bank_mask:0xf
	s_nop 0
	v_add_f32_dpp v48, v48, v48 quad_perm:[2,3,0,1] row_mask:0xf bank_mask:0xf
	v_add_f32_dpp v49, v49, v49 quad_perm:[2,3,0,1] row_mask:0xf bank_mask:0xf
	s_nop 0
	v_add_f32_dpp v48, v48, v48 quad_perm:[1,0,3,2] row_mask:0xf bank_mask:0xf
	v_add_f32_dpp v49, v49, v49 quad_perm:[1,0,3,2] row_mask:0xf bank_mask:0xf
	v_mov_b32_e32 v0, 0x3727c5ac
	s_nop 0
	v_pk_fma_f32 v[48:49], v[48:49], s[0:1], v[0:1] op_sel_hi:[1,0,0]
	s_nop 0
	v_mul_f32_e32 v0, 0x4b800000, v49
	v_cmp_gt_f32_e64 s[40:41], s2, v49
	v_cmp_gt_f32_e64 s[0:1], s2, v48
	s_nop 0
	v_cndmask_b32_e64 v0, v49, v0, s[40:41]
	v_rsq_f32_e32 v0, v0
	s_nop 0
	v_mul_f32_e32 v47, 0x45800000, v0
	v_cndmask_b32_e64 v0, v0, v47, s[40:41]
	v_mul_f32_e32 v47, 0x4b800000, v48
	v_cndmask_b32_e64 v47, v48, v47, s[0:1]
	v_rsq_f32_e32 v47, v47
	s_nop 0
	v_mul_f32_e32 v48, 0x45800000, v47
	v_cndmask_b32_e64 v47, v47, v48, s[0:1]
	s_and_saveexec_b64 s[0:1], vcc
	s_cbranch_execz .LBB0_149
	v_readlane_b32 s4, v254, 30
	v_readlane_b32 s5, v254, 31
	v_mul_f32_e32 v56, 0x3a800000, v46
	v_mov_b32_e32 v57, v0
	v_lshl_add_u64 v[48:49], v[44:45], 3, s[4:5]
	global_store_dwordx2 v[48:49], v[56:57], off
	s_and_b64 exec, exec, s[38:39]
	s_cbranch_execz .LBB0_149
	v_mul_f32_e32 v46, 0x3a800000, v43
	v_lshl_add_u64 v[48:49], s[42:43], 3, v[48:49]
	global_store_dwordx2 v[48:49], v[46:47], off

.Lxb4_loop:
	global_load_dwordx4 v[12:15], v[2:3], off offset:16 nt
	global_load_dwordx4 v[16:19], v[2:3], off nt
	v_lshl_add_u64 v[2:3], v[2:3], 0, s[40:41]
	v_lshl_add_u64 v[6:7], v[6:7], 0, s[38:39]
	global_load_dwordx4 v[20:23], v[2:3], off offset:16 nt
	global_load_dwordx4 v[24:27], v[2:3], off nt
	v_lshl_add_u64 v[2:3], v[2:3], 0, s[40:41]
	v_lshl_add_u64 v[6:7], v[6:7], 0, s[38:39]
	global_load_dwordx4 v[28:31], v[2:3], off offset:16 nt
	global_load_dwordx4 v[32:35], v[2:3], off nt
	v_lshl_add_u64 v[2:3], v[2:3], 0, s[40:41]
	v_lshl_add_u64 v[6:7], v[6:7], 0, s[38:39]
	global_load_dwordx4 v[36:39], v[2:3], off offset:16 nt
	global_load_dwordx4 v[40:43], v[2:3], off nt
	v_lshl_add_u64 v[2:3], v[2:3], 0, s[40:41]
	v_lshl_add_u64 v[6:7], v[6:7], 0, s[38:39]
	s_mov_b64 s[4:5], 0x3fffff
	v_cmp_lt_u64_e32 vcc, s[4:5], v[6:7]
	s_or_b64 s[42:43], vcc, s[42:43]
	s_waitcnt vmcnt(6)
	v_cvt_pk_bf16_f32 v15, v14, v15
	v_cvt_pk_bf16_f32 v14, v12, v13
	v_cvt_pk_bf16_f32 v13, v18, v19
	v_cvt_pk_bf16_f32 v12, v16, v17
	global_store_dwordx4 v[4:5], v[12:15], off
	v_lshl_add_u64 v[4:5], v[4:5], 0, s[28:29]
	s_waitcnt vmcnt(5)
	v_cvt_pk_bf16_f32 v23, v22, v23
	v_cvt_pk_bf16_f32 v22, v20, v21
	v_cvt_pk_bf16_f32 v21, v26, v27
	v_cvt_pk_bf16_f32 v20, v24, v25
	global_store_dwordx4 v[4:5], v[20:23], off
	v_lshl_add_u64 v[4:5], v[4:5], 0, s[28:29]
	s_waitcnt vmcnt(4)
	v_cvt_pk_bf16_f32 v31, v30, v31
	v_cvt_pk_bf16_f32 v30, v28, v29
	v_cvt_pk_bf16_f32 v29, v34, v35
	v_cvt_pk_bf16_f32 v28, v32, v33
	global_store_dwordx4 v[4:5], v[28:31], off
	v_lshl_add_u64 v[4:5], v[4:5], 0, s[28:29]
	s_waitcnt vmcnt(3)
	v_cvt_pk_bf16_f32 v39, v38, v39
	v_cvt_pk_bf16_f32 v38, v36, v37
	v_cvt_pk_bf16_f32 v37, v42, v43
	v_cvt_pk_bf16_f32 v36, v40, v41
	global_store_dwordx4 v[4:5], v[36:39], off
	v_lshl_add_u64 v[4:5], v[4:5], 0, s[28:29]
	s_andn2_b64 exec, exec, s[42:43]
	s_cbranch_execnz .Lxb4_loop
	s_branch .LBB0_744
